# v118 + P3 projection GEMM epilogues (CK pitch 2048, CVT pitch 4096): stores re-laid to quad-contiguous 64-B pieces like the other GEMM phases (P3's critical path)
# speedup vs baseline: 1.0094x; 1.0030x over previous
; #define PG8_BAR __builtin_amdgcn_s_barrier()
; template <class Epi, class Sched, bool ALIGN_EPI = false, bool SP2 = false>
; __device__ __forceinline__ void gemm_phase(PG8_LAS unsigned char* lds, const Gemm g, const Sched& S, const Epi& E, const int wv  ) {
;     ...
;     const int tid = tid_, wid = __builtin_amdgcn_readfirstlane(tid >> 6), lane = tid & 63, wr = wid >> 2, wc = wid & 3, fr = lane & 15, fq = lane >> 4;
;     const int K = g.K, nt = K / BK;
;     unsigned voffA[2], voffB[2];
; #pragma unroll
;     for (int i = 0; i < 2; ++i) { int R, C; stage_rc(tid * 16 + i * 8192, R, C); const int Rb = Epi::PERM ? ((R & ~31) + perm32(R & 31)) : R;
;         voffA[i] = (unsigned)(R * K + C) * 2u; voffB[i] = (unsigned)(Rb * K + C) * 2u; }
;     const size_t kstep = (size_t)(BK * 2);
;     const size_t hstep = (size_t)HALF * K * 2;
;     const size_t tstep = 2 * hstep;
;     const unsigned ldsw = (unsigned)wid * 1024u;
;     const int aoff = lds_byte(wr * 64 + fr, fq * 8), boff = lds_byte(wc * 32 + fr, fq * 8);
;     ...
;     Unit cur, nxt; int ui = 0;
;     if (!S.next(0, cur)) return;
;     f32x4 acc[2][2][4][2];
; #pragma unroll
;     for (int a = 0; a < 2; ++a)
; #pragma unroll
;         for (int b = 0; b < 2; ++b)
; #pragma unroll
;             for (int m = 0; m < 4; ++m)
; #pragma unroll
;                 for (int n = 0; n < 2; ++n) acc[a][b][m][n] = (f32x4){0.f, 0.f, 0.f, 0.f};
;     bf16x8 At[4][2], B0[2][2], B1[2][2];
;     const char* cA = (const char*)g.A + (size_t)cur.pm * tstep; const char* cB = (const char*)g.Bt + (size_t)cur.pn * tstep;
;     S.a_ready(cur);
;     if constexpr (SP2) {
;         PG8_STAGE(PG8_SB(0, 0), cB, voffB); PG8_STAGE(PG8_SB(0, 1), cB + hstep, voffB); PG8_STAGE(PG8_SA(0, 0), cA, voffA); PG8_STAGE(PG8_SA(0, 1), cA + hstep, voffA);
;         if (wr == 1) PG8_BAR;
;         PG8_WAIT_V(2); PG8_BAR;
;         PG8_STAGE(PG8_SB(1, 0), cB + kstep, voffB); PG8_STAGE(PG8_SA(1, 0), cA + kstep, voffA); PG8_STAGE(PG8_SB(1, 1), cB + hstep + kstep, voffB);
;         PG8_WAIT_V(6); PG8_BAR;
; __global__ void __launch_bounds__(NWAVES * 64, 2) mk_fwd(Params P) {
;     ...
;         LANE_TID;
;         if (bx < 64) {
;         { pg8::Gemm g{MEMN, Wckv_t, MM, D, D}; pg8::StaticOrder S; S.init(MM, D, G, bx);
;           pg8::EpiBf16<0> E{CKb, D, nullptr, 0, 0, 1.f};
;           pg8::gemm_phase<pg8::EpiBf16<0>, pg8::StaticOrder, true, true>(lds, g, S, E, wave); }
.LBB0_799:
	s_cmp_lt_i32 s74, 4
	s_cselect_b64 s[2:3], -1, 0
	s_and_b64 s[6:7], s[2:3], s[0:1]
	s_andn2_b64 vcc, exec, s[6:7]
	s_cbranch_vccnz .LBB0_848
	v_and_b32_e32 v248, 15, v212
	v_lshrrev_b32_e32 v249, 2, v212
	v_sub_u32_e32 v249, v249, v248
	v_lshrrev_b32_e32 v248, 4, v212
	v_and_b32_e32 v253, 3, v212
	v_sub_u32_e32 v248, v253, v248
	v_lshlrev_b32_e32 v248, 4, v248
	v_mul_i32_i24_e32 v250, 0x800, v249
	v_add_u32_e32 v250, v250, v248
	v_ashrrev_i32_e32 v251, 31, v250
	v_mul_i32_i24_e32 v249, 0x1000, v249
	v_add_u32_e32 v248, v249, v248
	v_ashrrev_i32_e32 v249, 31, v248
	v_lshlrev_b32_e32 v253, 4, v253
	v_lshrrev_b32_e32 v252, 2, v212
	v_add_u32_e32 v253, v253, v252
	v_lshlrev_b32_e32 v253, 2, v253
	s_cmp_lt_i32 s88, 64
	s_cselect_b64 s[0:1], -1, 0
	s_cmp_gt_i32 s88, 63
	v_mov_b32_e32 v128, v212
	s_cbranch_scc1 .LBB0_845
	s_add_u32 s2, s72, 0x1b800000
	s_addc_u32 s3, s73, 0
	s_and_b32 s21, s93, 0xffffffc0
	v_mov_b32_e32 v8, v212
	s_ashr_i32 s20, s82, 31
	s_cmp_gt_i32 s88, 31
	v_add_u32_e32 v0, s21, v8
	s_nop 0
	v_readfirstlane_b32 s15, v0
	s_cbranch_scc1 .LBB0_821
	s_waitcnt lgkmcnt(0)
	v_lshlrev_b32_e32 v1, 4, v0
	v_add_u32_e32 v2, 0x2000, v1
	v_ashrrev_i32_e32 v3, 31, v2
	v_lshrrev_b32_e32 v3, 22, v3
	v_add_u32_e32 v3, v2, v3
	v_ashrrev_i32_e32 v9, 10, v3
	v_mul_i32_i24_e32 v3, 0x400, v9
	v_sub_u32_e32 v2, v2, v3
	v_lshrrev_b32_e32 v3, 4, v2
	v_bitop3_b32 v2, v3, v2, 32 bitop3:0x6c
	v_ashrrev_i32_e32 v3, 31, v2
	v_lshrrev_b32_e32 v3, 26, v3
	s_ashr_i32 s10, s15, 6
	v_add_u32_e32 v3, v2, v3
	v_lshlrev_b32_e32 v4, 3, v9
	s_ashr_i32 s16, s15, 8
	s_lshl_b32 s33, s10, 10
	v_ashrrev_i32_e32 v10, 6, v3
	v_and_b32_e32 v4, -16, v4
	s_add_u32 s36, s72, 0x1a200000
	v_add_u32_e32 v4, v10, v4
	s_addc_u32 s37, s73, 0
	s_ashr_i32 s38, s88, 31
	v_and_b32_e32 v5, 3, v10
	s_mov_b32 s9, 0x1fffe0
	v_lshrrev_b32_e32 v6, 2, v4
	v_lshlrev_b32_e32 v7, 1, v4
	v_and_b32_e32 v3, 0xc0, v3
	s_lshr_b32 s4, s38, 29
	v_and_or_b32 v5, v4, s9, v5
	v_and_b32_e32 v6, 4, v6
	v_and_b32_e32 v7, 24, v7
	v_sub_u32_e32 v2, v2, v3
	v_mov_b32_e32 v3, 1
	s_add_i32 s4, s88, s4
	v_or3_b32 v5, v5, v6, v7
	v_lshlrev_b32_e32 v6, 5, v9
	v_ashrrev_i16_sdwa v2, v3, sext(v2) dst_sel:DWORD dst_unused:UNUSED_PAD src0_sel:DWORD src1_sel:BYTE_0
	s_ashr_i32 s5, s4, 3
	s_and_b32 s4, s4, -8
	v_and_b32_e32 v6, 32, v6
	v_bfe_i32 v11, v2, 0, 16
	s_sub_i32 s4, s88, s4
	v_add_lshl_u32 v2, v6, v11, 1
	s_lshl_b32 s8, s4, 2
	v_lshl_add_u32 v130, v5, 11, v2
	v_lshl_add_u32 v132, v4, 11, v2
	v_bfe_i32 v2, v0, 27, 1
	s_cmp_lt_i32 s4, 0
	s_mul_i32 s4, s4, 5
	v_lshrrev_b32_e32 v2, 22, v2
	v_add_u32_e32 v2, v1, v2
	s_cselect_b32 s4, s4, s8
	v_and_b32_e32 v2, 0xfffffc00, v2
	s_add_i32 s4, s4, s5
	v_sub_u32_e32 v1, v1, v2
	s_ashr_i32 s5, s4, 31
	v_lshrrev_b32_e32 v2, 4, v1
	v_ashrrev_i32_e32 v4, 31, v0
	s_lshr_b32 s5, s5, 27
	v_bitop3_b32 v1, v2, v1, 32 bitop3:0x6c
	v_lshrrev_b32_e32 v4, 26, v4
	s_add_i32 s5, s4, s5
	v_ashrrev_i32_e32 v2, 31, v1
	v_add_u32_e32 v0, v0, v4
	s_ashr_i32 s8, s5, 5
	s_andn2_b32 s5, s5, 31
	v_lshrrev_b32_e32 v2, 26, v2
	v_ashrrev_i32_e32 v13, 6, v0
	s_sub_i32 s4, s4, s5
	v_add_u32_e32 v2, v1, v2
	v_lshlrev_b32_e32 v0, 3, v13
	s_bfe_i32 s5, s4, 0x80000
	v_ashrrev_i32_e32 v12, 6, v2
	v_and_b32_e32 v0, -16, v0
	s_bfe_u32 s5, s5, 0x3000c
	v_add_u32_e32 v0, v12, v0
	v_and_b32_e32 v4, 3, v12
	s_add_i32 s5, s4, s5
	v_and_or_b32 v4, v0, s9, v4
	s_bfe_i32 s9, s5, 0x80000
	s_and_b32 s5, s5, 0xf8
	s_sub_i32 s4, s4, s5
	s_lshl_b32 s8, s8, 3
	s_sext_i32_i16 s9, s9
	s_sext_i32_i8 s4, s4
	v_lshrrev_b32_e32 v5, 2, v0
	v_lshlrev_b32_e32 v6, 1, v0
	v_and_b32_e32 v2, 0xc0, v2
	s_lshr_b32 s14, s9, 3
	s_lshr_b32 s14, s88, 3
	s_add_i32 s42, s8, s4
	s_and_b32 s42, s88, 7
	v_and_b32_e32 v5, 4, v5
	v_and_b32_e32 v6, 24, v6
	v_sub_u32_e32 v1, v1, v2
	s_ashr_i32 s43, s42, 31
	s_bfe_i64 s[8:9], s[14:15], 0x100000
	v_or3_b32 v4, v4, v5, v6
	v_lshlrev_b32_e32 v5, 5, v13
	v_ashrrev_i16_sdwa v1, v3, sext(v1) dst_sel:DWORD dst_unused:UNUSED_PAD src0_sel:DWORD src1_sel:BYTE_0
	s_lshl_b64 s[4:5], s[42:43], 19
	s_lshl_b64 s[8:9], s[8:9], 19
	v_and_b32_e32 v5, 32, v5
	v_bfe_i32 v14, v1, 0, 16
	s_add_u32 s46, s36, s8
	v_add_lshl_u32 v1, v5, v14, 1
	s_addc_u32 s47, s37, s9
	s_add_i32 s39, s33, 0
	v_lshl_add_u32 v134, v4, 11, v1
	s_add_i32 m0, s39, 0x10000
	v_lshl_add_u32 v136, v0, 11, v1
	global_load_lds_dwordx4 v134, s[46:47]
	s_add_i32 m0, s39, 0x12000
	s_add_u32 s8, s46, 0x40000
	global_load_lds_dwordx4 v130, s[46:47]
	s_addc_u32 s9, s47, 0
	s_add_i32 m0, s39, 0x14000
	v_mov_b32_e32 v135, 0
	global_load_lds_dwordx4 v134, s[8:9]
	s_add_i32 m0, s39, 0x16000
	s_add_u32 s44, s2, s4
	s_addc_u32 s45, s3, s5
	s_add_i32 s40, s39, 0x2000
	global_load_lds_dwordx4 v130, s[8:9]
	s_mov_b32 m0, s39
	s_add_u32 s4, s44, 0x40000
	global_load_lds_dwordx4 v136, s[44:45]
	s_mov_b32 m0, s40
	s_addc_u32 s5, s45, 0
	s_add_i32 s41, s39, 0x4000
	global_load_lds_dwordx4 v132, s[44:45]
	s_mov_b32 m0, s41
	s_add_i32 s43, s39, 0x6000
	global_load_lds_dwordx4 v136, s[4:5]
	s_mov_b32 m0, s43
	v_mov_b32_e32 v131, v135
	global_load_lds_dwordx4 v132, s[4:5]
	v_mov_b32_e32 v137, v135
	v_mov_b32_e32 v133, v135
	s_cmp_eq_u32 s16, 1
	s_mov_b32 s50, 0
	v_lshl_add_u64 v[6:7], s[46:47], 0, v[134:135]
	v_lshl_add_u64 v[2:3], s[46:47], 0, v[130:131]
	s_mov_b64 s[4:5], 0x40000
	v_lshl_add_u64 v[0:1], s[44:45], 0, v[136:137]
	s_cselect_b64 s[8:9], -1, 0
	s_cmp_lg_u32 s16, 1
	v_lshl_add_u64 v[4:5], s[44:45], 0, v[132:133]
	s_cbranch_scc1 .LBB0_804
	s_barrier

; __device__ __forceinline__ unsigned cvt_pk_bf16(float lo, float hi) { unsigned r; asm volatile("v_cvt_pk_bf16_f32 %0, %1, %2" : "=v"(r) : "v"(lo), "v"(hi)); return r; }
;     __device__ __forceinline__ void operator()(const f32x4 (&acc)[2][2][4][2], const Unit& u, int wr, int wc, int fr, int fq) const {
;     ...
;         for (int ai = 0; ai < 2; ++ai)
; #pragma unroll
;             for (int m = 0; m < 4; ++m) { bf16_t* rowp = base + (size_t)(row0 + ai * HALF + m * 16) * ldc + col0;
; #pragma unroll
;                 for (int bj = 0; bj < 2; ++bj) { f32x4 v0 = acc[ai][bj][m][0] + bv[bj][0], v1 = acc[ai][bj][m][1] + bv[bj][1];
;                     if (ACT == 1) { f32x2 a = gelu_pk((f32x2){v0[0], v0[1]}), b = gelu_pk((f32x2){v0[2], v0[3]}), c = gelu_pk((f32x2){v1[0], v1[1]}), d = gelu_pk((f32x2){v1[2], v1[3]});
;                         v0 = (f32x4){a.x, a.y, b.x, b.y}; v1 = (f32x4){c.x, c.y, d.x, d.y}; }
;                     v0 = v0 * sc; v1 = v1 * sc; u32x4 w; w.x = cvt_pk_bf16(v0[0], v0[1]); w.y = cvt_pk_bf16(v0[2], v0[3]); w.z = cvt_pk_bf16(v1[0], v1[1]); w.w = cvt_pk_bf16(v1[2], v1[3]);
;                     *(u32x4*)(rowp + bj * HALF) = w; } }
.LBB0_817:
	v_lshl_add_u32 v150, s42, 8, v129
	v_lshl_or_b32 v142, s59, 8, v145
	v_ashrrev_i32_e32 v143, 31, v142
	v_ashrrev_i32_e32 v151, 31, v150
	v_lshl_add_u64 v[152:153], v[142:143], 1, s[10:11]
	v_lshlrev_b64 v[142:143], 11, v[150:151]
	v_lshl_add_u64 v[142:143], v[152:153], 0, v[142:143]
	v_pk_add_f32 v[126:127], v[126:127], 0 op_sel_hi:[1,0]
	v_pk_add_f32 v[124:125], v[124:125], 0 op_sel_hi:[1,0]
	v_pk_add_f32 v[154:155], v[122:123], 0 op_sel_hi:[1,0]
	v_pk_add_f32 v[122:123], v[120:121], 0 op_sel_hi:[1,0]
	v_cvt_pk_bf16_f32 v120, v124, v125
	v_cvt_pk_bf16_f32 v121, v126, v127
	v_pk_add_f32 v[116:117], v[116:117], 0 op_sel_hi:[1,0]
	v_cvt_pk_bf16_f32 v122, v122, v123
	v_cvt_pk_bf16_f32 v123, v154, v155
	ds_bpermute_b32 v240, v253, v120
	ds_bpermute_b32 v241, v253, v121
	ds_bpermute_b32 v242, v253, v122
	ds_bpermute_b32 v243, v253, v123
	v_lshl_add_u64 v[236:237], v[142:143], 0, v[250:251]
	v_pk_add_f32 v[118:119], v[118:119], 0 op_sel_hi:[1,0]
	v_pk_add_f32 v[112:113], v[112:113], 0 op_sel_hi:[1,0]
	v_pk_add_f32 v[120:121], v[110:111], 0 op_sel_hi:[1,0]
	v_pk_add_f32 v[110:111], v[108:109], 0 op_sel_hi:[1,0]
	v_cvt_pk_bf16_f32 v108, v116, v117
	v_cvt_pk_bf16_f32 v109, v118, v119
	v_pk_add_f32 v[100:101], v[100:101], 0 op_sel_hi:[1,0]
	v_cvt_pk_bf16_f32 v110, v110, v111
	v_cvt_pk_bf16_f32 v111, v120, v121
	ds_bpermute_b32 v244, v253, v108
	ds_bpermute_b32 v245, v253, v109
	ds_bpermute_b32 v246, v253, v110
	ds_bpermute_b32 v247, v253, v111
	v_lshl_add_u64 v[238:239], v[142:143], 0, v[250:251]
	s_waitcnt lgkmcnt(4)
	global_store_dwordx4 v[236:237], v[240:243], off
	v_pk_add_f32 v[102:103], v[102:103], 0 op_sel_hi:[1,0]
	v_pk_add_f32 v[96:97], v[96:97], 0 op_sel_hi:[1,0]
	v_or_b32_e32 v108, 16, v150
	v_ashrrev_i32_e32 v109, 31, v108
	v_lshlrev_b64 v[108:109], 11, v[108:109]
	v_lshl_add_u64 v[108:109], v[152:153], 0, v[108:109]
	v_pk_add_f32 v[110:111], v[114:115], 0 op_sel_hi:[1,0]
	v_pk_add_f32 v[114:115], v[106:107], 0 op_sel_hi:[1,0]
	v_pk_add_f32 v[106:107], v[104:105], 0 op_sel_hi:[1,0]
	v_cvt_pk_bf16_f32 v104, v112, v113
	v_cvt_pk_bf16_f32 v105, v110, v111
	v_pk_add_f32 v[84:85], v[84:85], 0 op_sel_hi:[1,0]
	v_cvt_pk_bf16_f32 v106, v106, v107
	v_cvt_pk_bf16_f32 v107, v114, v115
	ds_bpermute_b32 v240, v253, v104
	ds_bpermute_b32 v241, v253, v105
	ds_bpermute_b32 v242, v253, v106
	ds_bpermute_b32 v243, v253, v107
	v_lshl_add_u64 v[236:237], v[108:109], 0, v[250:251]
	s_waitcnt lgkmcnt(4)
	global_store_dwordx4 v[238:239], v[244:247], off offset:256
	v_pk_add_f32 v[86:87], v[86:87], 0 op_sel_hi:[1,0]
	v_pk_add_f32 v[80:81], v[80:81], 0 op_sel_hi:[1,0]
	v_pk_add_f32 v[104:105], v[94:95], 0 op_sel_hi:[1,0]
	v_pk_add_f32 v[94:95], v[92:93], 0 op_sel_hi:[1,0]
	v_cvt_pk_bf16_f32 v92, v100, v101
	v_cvt_pk_bf16_f32 v93, v102, v103
	v_pk_add_f32 v[70:71], v[70:71], 0 op_sel_hi:[1,0]
	v_cvt_pk_bf16_f32 v94, v94, v95
	v_cvt_pk_bf16_f32 v95, v104, v105
	ds_bpermute_b32 v244, v253, v92
	ds_bpermute_b32 v245, v253, v93
	ds_bpermute_b32 v246, v253, v94
	ds_bpermute_b32 v247, v253, v95
	v_lshl_add_u64 v[238:239], v[108:109], 0, v[250:251]
	s_waitcnt lgkmcnt(4)
	global_store_dwordx4 v[236:237], v[240:243], off
	v_pk_add_f32 v[68:69], v[68:69], 0 op_sel_hi:[1,0]
	v_pk_add_f32 v[60:61], v[60:61], 0 op_sel_hi:[1,0]
	v_or_b32_e32 v92, 32, v150
	v_ashrrev_i32_e32 v93, 31, v92
	v_lshlrev_b64 v[92:93], 11, v[92:93]
	v_lshl_add_u64 v[92:93], v[152:153], 0, v[92:93]
	v_pk_add_f32 v[94:95], v[98:99], 0 op_sel_hi:[1,0]
	v_pk_add_f32 v[98:99], v[90:91], 0 op_sel_hi:[1,0]
	v_pk_add_f32 v[90:91], v[88:89], 0 op_sel_hi:[1,0]
	v_cvt_pk_bf16_f32 v88, v96, v97
	v_cvt_pk_bf16_f32 v89, v94, v95
	v_pk_add_f32 v[62:63], v[62:63], 0 op_sel_hi:[1,0]
	v_cvt_pk_bf16_f32 v90, v90, v91
	v_cvt_pk_bf16_f32 v91, v98, v99
	ds_bpermute_b32 v240, v253, v88
	ds_bpermute_b32 v241, v253, v89
	ds_bpermute_b32 v242, v253, v90
	ds_bpermute_b32 v243, v253, v91
	v_lshl_add_u64 v[236:237], v[92:93], 0, v[250:251]
	s_waitcnt lgkmcnt(4)
	global_store_dwordx4 v[238:239], v[244:247], off offset:256
	v_pk_add_f32 v[54:55], v[54:55], 0 op_sel_hi:[1,0]
	v_pk_add_f32 v[52:53], v[52:53], 0 op_sel_hi:[1,0]
	v_pk_add_f32 v[88:89], v[78:79], 0 op_sel_hi:[1,0]
	v_pk_add_f32 v[78:79], v[76:77], 0 op_sel_hi:[1,0]
	v_cvt_pk_bf16_f32 v76, v84, v85
	v_cvt_pk_bf16_f32 v77, v86, v87
	v_pk_add_f32 v[48:49], v[48:49], 0 op_sel_hi:[1,0]
	v_cvt_pk_bf16_f32 v78, v78, v79
	v_cvt_pk_bf16_f32 v79, v88, v89
	ds_bpermute_b32 v244, v253, v76
	ds_bpermute_b32 v245, v253, v77
	ds_bpermute_b32 v246, v253, v78
	ds_bpermute_b32 v247, v253, v79
	v_lshl_add_u64 v[238:239], v[92:93], 0, v[250:251]
	s_waitcnt lgkmcnt(4)
	global_store_dwordx4 v[236:237], v[240:243], off
	v_pk_add_f32 v[38:39], v[38:39], 0 op_sel_hi:[1,0]
	v_pk_add_f32 v[36:37], v[36:37], 0 op_sel_hi:[1,0]
	v_or_b32_e32 v76, 48, v150
	v_ashrrev_i32_e32 v77, 31, v76
	v_lshlrev_b64 v[76:77], 11, v[76:77]
	v_lshl_add_u64 v[76:77], v[152:153], 0, v[76:77]
	v_pk_add_f32 v[78:79], v[82:83], 0 op_sel_hi:[1,0]
	v_pk_add_f32 v[82:83], v[74:75], 0 op_sel_hi:[1,0]
	v_pk_add_f32 v[74:75], v[72:73], 0 op_sel_hi:[1,0]
	v_cvt_pk_bf16_f32 v72, v80, v81
	v_cvt_pk_bf16_f32 v73, v78, v79
	v_pk_add_f32 v[32:33], v[32:33], 0 op_sel_hi:[1,0]
	v_cvt_pk_bf16_f32 v74, v74, v75
	v_cvt_pk_bf16_f32 v75, v82, v83
	ds_bpermute_b32 v240, v253, v72
	ds_bpermute_b32 v241, v253, v73
	ds_bpermute_b32 v242, v253, v74
	ds_bpermute_b32 v243, v253, v75
	v_lshl_add_u64 v[236:237], v[76:77], 0, v[250:251]
	s_waitcnt lgkmcnt(4)
; __device__ __forceinline__ unsigned cvt_pk_bf16(float lo, float hi) { unsigned r; asm volatile("v_cvt_pk_bf16_f32 %0, %1, %2" : "=v"(r) : "v"(lo), "v"(hi)); return r; }
; #define PG8_BAR __builtin_amdgcn_s_barrier()
;     __device__ __forceinline__ void operator()(const f32x4 (&acc)[2][2][4][2], const Unit& u, int wr, int wc, int fr, int fq) const {
;     ...
;         for (int ai = 0; ai < 2; ++ai)
; #pragma unroll
;             for (int m = 0; m < 4; ++m) { bf16_t* rowp = base + (size_t)(row0 + ai * HALF + m * 16) * ldc + col0;
; #pragma unroll
;                 for (int bj = 0; bj < 2; ++bj) { f32x4 v0 = acc[ai][bj][m][0] + bv[bj][0], v1 = acc[ai][bj][m][1] + bv[bj][1];
;                     if (ACT == 1) { f32x2 a = gelu_pk((f32x2){v0[0], v0[1]}), b = gelu_pk((f32x2){v0[2], v0[3]}), c = gelu_pk((f32x2){v1[0], v1[1]}), d = gelu_pk((f32x2){v1[2], v1[3]});
;                         v0 = (f32x4){a.x, a.y, b.x, b.y}; v1 = (f32x4){c.x, c.y, d.x, d.y}; }
;                     v0 = v0 * sc; v1 = v1 * sc; u32x4 w; w.x = cvt_pk_bf16(v0[0], v0[1]); w.y = cvt_pk_bf16(v0[2], v0[3]); w.z = cvt_pk_bf16(v1[0], v1[1]); w.w = cvt_pk_bf16(v1[2], v1[3]);
;                     *(u32x4*)(rowp + bj * HALF) = w; } }
; template <class Epi, class Sched, bool ALIGN_EPI = false, bool SP2 = false>
; __device__ __forceinline__ void gemm_phase(PG8_LAS unsigned char* lds, const Gemm g, const Sched& S, const Epi& E, const int wv  ) {
;     ...
;         if constexpr (!Epi::AFTER_DRAIN) { E(acc, cur, wr, wc, fr, fq); S.done(cur); }
;         if (!has_next) break;
; #pragma unroll
;         for (int a = 0; a < 2; ++a)
; #pragma unroll
;             for (int b = 0; b < 2; ++b)
; #pragma unroll
;                 for (int m = 0; m < 4; ++m)
; #pragma unroll
;                     for (int n = 0; n < 2; ++n) acc[a][b][m][n] = (f32x4){0.f, 0.f, 0.f, 0.f};
;         cur = nxt; cA = nA; cB = nB; ++ui;
;         if constexpr (ALIGN_EPI) { if (wr == 1) PG8_BAR; }
;     }
	global_store_dwordx4 v[238:239], v[244:247], off offset:256
	v_pk_add_f32 v[22:23], v[22:23], 0 op_sel_hi:[1,0]
	v_pk_add_f32 v[20:21], v[20:21], 0 op_sel_hi:[1,0]
	v_pk_add_f32 v[72:73], v[66:67], 0 op_sel_hi:[1,0]
	v_pk_add_f32 v[66:67], v[64:65], 0 op_sel_hi:[1,0]
	v_cvt_pk_bf16_f32 v64, v68, v69
	v_cvt_pk_bf16_f32 v65, v70, v71
	v_pk_add_f32 v[16:17], v[16:17], 0 op_sel_hi:[1,0]
	v_cvt_pk_bf16_f32 v66, v66, v67
	v_cvt_pk_bf16_f32 v67, v72, v73
	ds_bpermute_b32 v244, v253, v64
	ds_bpermute_b32 v245, v253, v65
	ds_bpermute_b32 v246, v253, v66
	ds_bpermute_b32 v247, v253, v67
	v_lshl_add_u64 v[238:239], v[76:77], 0, v[250:251]
	s_waitcnt lgkmcnt(4)
	global_store_dwordx4 v[236:237], v[240:243], off
	v_pk_add_f32 v[6:7], v[6:7], 0 op_sel_hi:[1,0]
	v_pk_add_f32 v[4:5], v[4:5], 0 op_sel_hi:[1,0]
	v_pk_add_f32 v[66:67], v[58:59], 0 op_sel_hi:[1,0]
	v_pk_add_f32 v[58:59], v[56:57], 0 op_sel_hi:[1,0]
	v_cvt_pk_bf16_f32 v56, v60, v61
	v_add_co_u32_e32 v60, vcc, s55, v142
	v_cvt_pk_bf16_f32 v57, v62, v63
	v_cvt_pk_bf16_f32 v58, v58, v59
	v_cvt_pk_bf16_f32 v59, v66, v67
	v_lshl_add_u64 v[64:65], v[142:143], 0, s[4:5]
	s_nop 0
	v_addc_co_u32_e32 v61, vcc, 0, v143, vcc
	ds_bpermute_b32 v240, v253, v56
	ds_bpermute_b32 v241, v253, v57
	ds_bpermute_b32 v242, v253, v58
	ds_bpermute_b32 v243, v253, v59
	v_lshl_add_u64 v[236:237], v[60:61], 0, v[250:251]
	s_waitcnt lgkmcnt(4)
	global_store_dwordx4 v[238:239], v[244:247], off offset:256
	s_nop 1
	v_pk_add_f32 v[56:57], v[46:47], 0 op_sel_hi:[1,0]
	v_pk_add_f32 v[46:47], v[44:45], 0 op_sel_hi:[1,0]
	v_cvt_pk_bf16_f32 v44, v52, v53
	v_cvt_pk_bf16_f32 v45, v54, v55
	s_nop 0
	v_cvt_pk_bf16_f32 v46, v46, v47
	v_cvt_pk_bf16_f32 v47, v56, v57
	ds_bpermute_b32 v244, v253, v44
	ds_bpermute_b32 v245, v253, v45
	ds_bpermute_b32 v246, v253, v46
	ds_bpermute_b32 v247, v253, v47
	v_lshl_add_u64 v[238:239], v[64:65], 0, v[250:251]
	s_waitcnt lgkmcnt(4)
	global_store_dwordx4 v[236:237], v[240:243], off
	s_nop 1
	v_pk_add_f32 v[46:47], v[50:51], 0 op_sel_hi:[1,0]
	v_pk_add_f32 v[50:51], v[42:43], 0 op_sel_hi:[1,0]
	v_pk_add_f32 v[42:43], v[40:41], 0 op_sel_hi:[1,0]
	v_cvt_pk_bf16_f32 v40, v48, v49
	v_cvt_pk_bf16_f32 v41, v46, v47
	v_add_co_u32_e32 v46, vcc, s56, v142
	v_cvt_pk_bf16_f32 v42, v42, v43
	v_cvt_pk_bf16_f32 v43, v50, v51
	v_lshl_add_u64 v[44:45], v[142:143], 0, s[16:17]
	s_nop 0
	v_addc_co_u32_e32 v47, vcc, 0, v143, vcc
	ds_bpermute_b32 v240, v253, v40
	ds_bpermute_b32 v241, v253, v41
	ds_bpermute_b32 v242, v253, v42
	ds_bpermute_b32 v243, v253, v43
	v_lshl_add_u64 v[236:237], v[46:47], 0, v[250:251]
	s_waitcnt lgkmcnt(4)
	global_store_dwordx4 v[238:239], v[244:247], off offset:256
	s_nop 1
	v_pk_add_f32 v[40:41], v[30:31], 0 op_sel_hi:[1,0]
	v_pk_add_f32 v[30:31], v[28:29], 0 op_sel_hi:[1,0]
	v_cvt_pk_bf16_f32 v28, v36, v37
	v_cvt_pk_bf16_f32 v29, v38, v39
	s_nop 0
	v_cvt_pk_bf16_f32 v30, v30, v31
	v_cvt_pk_bf16_f32 v31, v40, v41
	ds_bpermute_b32 v244, v253, v28
	ds_bpermute_b32 v245, v253, v29
	ds_bpermute_b32 v246, v253, v30
	ds_bpermute_b32 v247, v253, v31
	v_lshl_add_u64 v[238:239], v[44:45], 0, v[250:251]
	s_waitcnt lgkmcnt(4)
	global_store_dwordx4 v[236:237], v[240:243], off
	s_nop 1
	v_pk_add_f32 v[30:31], v[34:35], 0 op_sel_hi:[1,0]
	v_pk_add_f32 v[34:35], v[26:27], 0 op_sel_hi:[1,0]
	v_pk_add_f32 v[26:27], v[24:25], 0 op_sel_hi:[1,0]
	v_cvt_pk_bf16_f32 v24, v32, v33
	v_cvt_pk_bf16_f32 v25, v30, v31
	v_add_co_u32_e32 v30, vcc, s57, v142
	v_cvt_pk_bf16_f32 v26, v26, v27
	v_cvt_pk_bf16_f32 v27, v34, v35
	v_lshl_add_u64 v[28:29], v[142:143], 0, s[18:19]
	s_nop 0
	v_addc_co_u32_e32 v31, vcc, 0, v143, vcc
	ds_bpermute_b32 v240, v253, v24
	ds_bpermute_b32 v241, v253, v25
	ds_bpermute_b32 v242, v253, v26
	ds_bpermute_b32 v243, v253, v27
	v_lshl_add_u64 v[236:237], v[30:31], 0, v[250:251]
	s_waitcnt lgkmcnt(4)
	global_store_dwordx4 v[238:239], v[244:247], off offset:256
	s_nop 1
	v_pk_add_f32 v[24:25], v[14:15], 0 op_sel_hi:[1,0]
	v_pk_add_f32 v[14:15], v[12:13], 0 op_sel_hi:[1,0]
	v_cvt_pk_bf16_f32 v12, v20, v21
	v_cvt_pk_bf16_f32 v13, v22, v23
	s_nop 0
	v_cvt_pk_bf16_f32 v14, v14, v15
	v_cvt_pk_bf16_f32 v15, v24, v25
	ds_bpermute_b32 v244, v253, v12
	ds_bpermute_b32 v245, v253, v13
	ds_bpermute_b32 v246, v253, v14
	ds_bpermute_b32 v247, v253, v15
	v_lshl_add_u64 v[238:239], v[28:29], 0, v[250:251]
	s_waitcnt lgkmcnt(4)
	global_store_dwordx4 v[236:237], v[240:243], off
	s_nop 1
	v_pk_add_f32 v[14:15], v[18:19], 0 op_sel_hi:[1,0]
	v_pk_add_f32 v[18:19], v[10:11], 0 op_sel_hi:[1,0]
	v_pk_add_f32 v[10:11], v[8:9], 0 op_sel_hi:[1,0]
	v_cvt_pk_bf16_f32 v8, v16, v17
	v_cvt_pk_bf16_f32 v9, v14, v15
	v_add_co_u32_e32 v14, vcc, s58, v142
	v_lshl_add_u64 v[12:13], v[142:143], 0, s[22:23]
	s_nop 0
	v_addc_co_u32_e32 v15, vcc, 0, v143, vcc
	v_cvt_pk_bf16_f32 v10, v10, v11
	v_cvt_pk_bf16_f32 v11, v18, v19
	ds_bpermute_b32 v240, v253, v8
	ds_bpermute_b32 v241, v253, v9
	ds_bpermute_b32 v242, v253, v10
	ds_bpermute_b32 v243, v253, v11
	v_lshl_add_u64 v[236:237], v[14:15], 0, v[250:251]
	s_waitcnt lgkmcnt(4)
	global_store_dwordx4 v[238:239], v[244:247], off offset:256
	s_andn2_b64 vcc, exec, s[24:25]
	s_mov_b64 s[24:25], -1
	v_pk_add_f32 v[8:9], v[2:3], 0 op_sel_hi:[1,0]
	v_pk_add_f32 v[2:3], v[0:1], 0 op_sel_hi:[1,0]
	v_cvt_pk_bf16_f32 v0, v4, v5
	v_cvt_pk_bf16_f32 v1, v6, v7
	s_nop 0
	v_cvt_pk_bf16_f32 v2, v2, v3
	v_cvt_pk_bf16_f32 v3, v8, v9
	ds_bpermute_b32 v244, v253, v0
	ds_bpermute_b32 v245, v253, v1
	ds_bpermute_b32 v246, v253, v2
	ds_bpermute_b32 v247, v253, v3
	v_lshl_add_u64 v[238:239], v[12:13], 0, v[250:251]
	s_waitcnt lgkmcnt(4)
	global_store_dwordx4 v[236:237], v[240:243], off
	s_waitcnt lgkmcnt(0)
	global_store_dwordx4 v[238:239], v[244:247], off offset:256
	s_cbranch_vccnz .LBB0_806
	s_andn2_b64 vcc, exec, s[8:9]
	s_cbranch_vccnz .LBB0_805
	s_barrier
	s_branch .LBB0_805

; __device__ __forceinline__ unsigned cvt_pk_bf16(float lo, float hi) { unsigned r; asm volatile("v_cvt_pk_bf16_f32 %0, %1, %2" : "=v"(r) : "v"(lo), "v"(hi)); return r; }
;     __device__ __forceinline__ void operator()(const f32x4 (&acc)[2][2][4][2], const Unit& u, int wr, int wc, int fr, int fq) const {
;     ...
;         for (int ai = 0; ai < 2; ++ai)
; #pragma unroll
;             for (int m = 0; m < 4; ++m) { bf16_t* rowp = base + (size_t)(row0 + ai * HALF + m * 16) * ldc + col0;
; #pragma unroll
;                 for (int bj = 0; bj < 2; ++bj) { f32x4 v0 = acc[ai][bj][m][0] + bv[bj][0], v1 = acc[ai][bj][m][1] + bv[bj][1];
;                     if (ACT == 1) { f32x2 a = gelu_pk((f32x2){v0[0], v0[1]}), b = gelu_pk((f32x2){v0[2], v0[3]}), c = gelu_pk((f32x2){v1[0], v1[1]}), d = gelu_pk((f32x2){v1[2], v1[3]});
;                         v0 = (f32x4){a.x, a.y, b.x, b.y}; v1 = (f32x4){c.x, c.y, d.x, d.y}; }
;                     v0 = v0 * sc; v1 = v1 * sc; u32x4 w; w.x = cvt_pk_bf16(v0[0], v0[1]); w.y = cvt_pk_bf16(v0[2], v0[3]); w.z = cvt_pk_bf16(v1[0], v1[1]); w.w = cvt_pk_bf16(v1[2], v1[3]);
;                     *(u32x4*)(rowp + bj * HALF) = w; } }
.LBB0_841:
	v_lshl_add_u32 v150, s42, 8, v129
	v_lshl_or_b32 v142, s59, 8, v145
	v_ashrrev_i32_e32 v143, 31, v142
	v_ashrrev_i32_e32 v151, 31, v150
	v_lshl_add_u64 v[152:153], v[142:143], 1, s[8:9]
	v_lshlrev_b64 v[142:143], 12, v[150:151]
	v_lshl_add_u64 v[142:143], v[152:153], 0, v[142:143]
	v_pk_add_f32 v[126:127], v[126:127], 0 op_sel_hi:[1,0]
	v_pk_add_f32 v[124:125], v[124:125], 0 op_sel_hi:[1,0]
	v_pk_add_f32 v[154:155], v[122:123], 0 op_sel_hi:[1,0]
	v_pk_add_f32 v[122:123], v[120:121], 0 op_sel_hi:[1,0]
	v_cvt_pk_bf16_f32 v120, v124, v125
	v_cvt_pk_bf16_f32 v121, v126, v127
	v_pk_add_f32 v[116:117], v[116:117], 0 op_sel_hi:[1,0]
	v_cvt_pk_bf16_f32 v122, v122, v123
	v_cvt_pk_bf16_f32 v123, v154, v155
	ds_bpermute_b32 v240, v253, v120
	ds_bpermute_b32 v241, v253, v121
	ds_bpermute_b32 v242, v253, v122
	ds_bpermute_b32 v243, v253, v123
	v_lshl_add_u64 v[236:237], v[142:143], 0, v[248:249]
	v_pk_add_f32 v[118:119], v[118:119], 0 op_sel_hi:[1,0]
	v_pk_add_f32 v[112:113], v[112:113], 0 op_sel_hi:[1,0]
	v_pk_add_f32 v[120:121], v[110:111], 0 op_sel_hi:[1,0]
	v_pk_add_f32 v[110:111], v[108:109], 0 op_sel_hi:[1,0]
	v_cvt_pk_bf16_f32 v108, v116, v117
	v_cvt_pk_bf16_f32 v109, v118, v119
	v_pk_add_f32 v[100:101], v[100:101], 0 op_sel_hi:[1,0]
	v_cvt_pk_bf16_f32 v110, v110, v111
	v_cvt_pk_bf16_f32 v111, v120, v121
	ds_bpermute_b32 v244, v253, v108
	ds_bpermute_b32 v245, v253, v109
	ds_bpermute_b32 v246, v253, v110
	ds_bpermute_b32 v247, v253, v111
	v_lshl_add_u64 v[238:239], v[142:143], 0, v[248:249]
	s_waitcnt lgkmcnt(4)
	global_store_dwordx4 v[236:237], v[240:243], off
	v_pk_add_f32 v[102:103], v[102:103], 0 op_sel_hi:[1,0]
	v_pk_add_f32 v[96:97], v[96:97], 0 op_sel_hi:[1,0]
	v_or_b32_e32 v108, 16, v150
	v_ashrrev_i32_e32 v109, 31, v108
	v_lshlrev_b64 v[108:109], 12, v[108:109]
	v_lshl_add_u64 v[108:109], v[152:153], 0, v[108:109]
	v_pk_add_f32 v[110:111], v[114:115], 0 op_sel_hi:[1,0]
	v_pk_add_f32 v[114:115], v[106:107], 0 op_sel_hi:[1,0]
	v_pk_add_f32 v[106:107], v[104:105], 0 op_sel_hi:[1,0]
	v_cvt_pk_bf16_f32 v104, v112, v113
	v_cvt_pk_bf16_f32 v105, v110, v111
	v_pk_add_f32 v[84:85], v[84:85], 0 op_sel_hi:[1,0]
	v_cvt_pk_bf16_f32 v106, v106, v107
	v_cvt_pk_bf16_f32 v107, v114, v115
	ds_bpermute_b32 v240, v253, v104
	ds_bpermute_b32 v241, v253, v105
	ds_bpermute_b32 v242, v253, v106
	ds_bpermute_b32 v243, v253, v107
	v_lshl_add_u64 v[236:237], v[108:109], 0, v[248:249]
	s_waitcnt lgkmcnt(4)
	global_store_dwordx4 v[238:239], v[244:247], off offset:256
	v_pk_add_f32 v[86:87], v[86:87], 0 op_sel_hi:[1,0]
	v_pk_add_f32 v[80:81], v[80:81], 0 op_sel_hi:[1,0]
	v_pk_add_f32 v[104:105], v[94:95], 0 op_sel_hi:[1,0]
	v_pk_add_f32 v[94:95], v[92:93], 0 op_sel_hi:[1,0]
	v_cvt_pk_bf16_f32 v92, v100, v101
	v_cvt_pk_bf16_f32 v93, v102, v103
	v_pk_add_f32 v[70:71], v[70:71], 0 op_sel_hi:[1,0]
	v_cvt_pk_bf16_f32 v94, v94, v95
	v_cvt_pk_bf16_f32 v95, v104, v105
	ds_bpermute_b32 v244, v253, v92
	ds_bpermute_b32 v245, v253, v93
	ds_bpermute_b32 v246, v253, v94
	ds_bpermute_b32 v247, v253, v95
	v_lshl_add_u64 v[238:239], v[108:109], 0, v[248:249]
	s_waitcnt lgkmcnt(4)
	global_store_dwordx4 v[236:237], v[240:243], off
	v_pk_add_f32 v[68:69], v[68:69], 0 op_sel_hi:[1,0]
	v_pk_add_f32 v[60:61], v[60:61], 0 op_sel_hi:[1,0]
	v_or_b32_e32 v92, 32, v150
	v_ashrrev_i32_e32 v93, 31, v92
	v_lshlrev_b64 v[92:93], 12, v[92:93]
	v_lshl_add_u64 v[92:93], v[152:153], 0, v[92:93]
	v_pk_add_f32 v[94:95], v[98:99], 0 op_sel_hi:[1,0]
	v_pk_add_f32 v[98:99], v[90:91], 0 op_sel_hi:[1,0]
	v_pk_add_f32 v[90:91], v[88:89], 0 op_sel_hi:[1,0]
	v_cvt_pk_bf16_f32 v88, v96, v97
	v_cvt_pk_bf16_f32 v89, v94, v95
	v_pk_add_f32 v[62:63], v[62:63], 0 op_sel_hi:[1,0]
	v_cvt_pk_bf16_f32 v90, v90, v91
	v_cvt_pk_bf16_f32 v91, v98, v99
	ds_bpermute_b32 v240, v253, v88
	ds_bpermute_b32 v241, v253, v89
	ds_bpermute_b32 v242, v253, v90
	ds_bpermute_b32 v243, v253, v91
	v_lshl_add_u64 v[236:237], v[92:93], 0, v[248:249]
	s_waitcnt lgkmcnt(4)
	global_store_dwordx4 v[238:239], v[244:247], off offset:256
	v_pk_add_f32 v[54:55], v[54:55], 0 op_sel_hi:[1,0]
	v_pk_add_f32 v[52:53], v[52:53], 0 op_sel_hi:[1,0]
	v_pk_add_f32 v[88:89], v[78:79], 0 op_sel_hi:[1,0]
	v_pk_add_f32 v[78:79], v[76:77], 0 op_sel_hi:[1,0]
	v_cvt_pk_bf16_f32 v76, v84, v85
	v_cvt_pk_bf16_f32 v77, v86, v87
	v_pk_add_f32 v[48:49], v[48:49], 0 op_sel_hi:[1,0]
	v_cvt_pk_bf16_f32 v78, v78, v79
	v_cvt_pk_bf16_f32 v79, v88, v89
	ds_bpermute_b32 v244, v253, v76
	ds_bpermute_b32 v245, v253, v77
	ds_bpermute_b32 v246, v253, v78
	ds_bpermute_b32 v247, v253, v79
	v_lshl_add_u64 v[238:239], v[92:93], 0, v[248:249]
	s_waitcnt lgkmcnt(4)
	global_store_dwordx4 v[236:237], v[240:243], off
	v_pk_add_f32 v[38:39], v[38:39], 0 op_sel_hi:[1,0]
	v_pk_add_f32 v[36:37], v[36:37], 0 op_sel_hi:[1,0]
	v_or_b32_e32 v76, 48, v150
	v_ashrrev_i32_e32 v77, 31, v76
	v_lshlrev_b64 v[76:77], 12, v[76:77]
	v_lshl_add_u64 v[76:77], v[152:153], 0, v[76:77]
	v_pk_add_f32 v[78:79], v[82:83], 0 op_sel_hi:[1,0]
	v_pk_add_f32 v[82:83], v[74:75], 0 op_sel_hi:[1,0]
	v_pk_add_f32 v[74:75], v[72:73], 0 op_sel_hi:[1,0]
	v_cvt_pk_bf16_f32 v72, v80, v81
	v_cvt_pk_bf16_f32 v73, v78, v79
	v_pk_add_f32 v[32:33], v[32:33], 0 op_sel_hi:[1,0]
	v_cvt_pk_bf16_f32 v74, v74, v75
	v_cvt_pk_bf16_f32 v75, v82, v83
	ds_bpermute_b32 v240, v253, v72
	ds_bpermute_b32 v241, v253, v73
	ds_bpermute_b32 v242, v253, v74
	ds_bpermute_b32 v243, v253, v75
	v_lshl_add_u64 v[236:237], v[76:77], 0, v[248:249]
	s_waitcnt lgkmcnt(4)
; __device__ __forceinline__ unsigned cvt_pk_bf16(float lo, float hi) { unsigned r; asm volatile("v_cvt_pk_bf16_f32 %0, %1, %2" : "=v"(r) : "v"(lo), "v"(hi)); return r; }
; #define PG8_BAR __builtin_amdgcn_s_barrier()
;     __device__ __forceinline__ void operator()(const f32x4 (&acc)[2][2][4][2], const Unit& u, int wr, int wc, int fr, int fq) const {
;     ...
;         for (int ai = 0; ai < 2; ++ai)
; #pragma unroll
;             for (int m = 0; m < 4; ++m) { bf16_t* rowp = base + (size_t)(row0 + ai * HALF + m * 16) * ldc + col0;
; #pragma unroll
;                 for (int bj = 0; bj < 2; ++bj) { f32x4 v0 = acc[ai][bj][m][0] + bv[bj][0], v1 = acc[ai][bj][m][1] + bv[bj][1];
;                     if (ACT == 1) { f32x2 a = gelu_pk((f32x2){v0[0], v0[1]}), b = gelu_pk((f32x2){v0[2], v0[3]}), c = gelu_pk((f32x2){v1[0], v1[1]}), d = gelu_pk((f32x2){v1[2], v1[3]});
;                         v0 = (f32x4){a.x, a.y, b.x, b.y}; v1 = (f32x4){c.x, c.y, d.x, d.y}; }
;                     v0 = v0 * sc; v1 = v1 * sc; u32x4 w; w.x = cvt_pk_bf16(v0[0], v0[1]); w.y = cvt_pk_bf16(v0[2], v0[3]); w.z = cvt_pk_bf16(v1[0], v1[1]); w.w = cvt_pk_bf16(v1[2], v1[3]);
;                     *(u32x4*)(rowp + bj * HALF) = w; } }
; template <class Epi, class Sched, bool ALIGN_EPI = false, bool SP2 = false>
; __device__ __forceinline__ void gemm_phase(PG8_LAS unsigned char* lds, const Gemm g, const Sched& S, const Epi& E, const int wv  ) {
;     ...
;         if constexpr (!Epi::AFTER_DRAIN) { E(acc, cur, wr, wc, fr, fq); S.done(cur); }
;         if (!has_next) break;
; #pragma unroll
;         for (int a = 0; a < 2; ++a)
; #pragma unroll
;             for (int b = 0; b < 2; ++b)
; #pragma unroll
;                 for (int m = 0; m < 4; ++m)
; #pragma unroll
;                     for (int n = 0; n < 2; ++n) acc[a][b][m][n] = (f32x4){0.f, 0.f, 0.f, 0.f};
;         cur = nxt; cA = nA; cB = nB; ++ui;
;         if constexpr (ALIGN_EPI) { if (wr == 1) PG8_BAR; }
;     }
	global_store_dwordx4 v[238:239], v[244:247], off offset:256
	v_pk_add_f32 v[22:23], v[22:23], 0 op_sel_hi:[1,0]
	v_pk_add_f32 v[20:21], v[20:21], 0 op_sel_hi:[1,0]
	v_pk_add_f32 v[72:73], v[66:67], 0 op_sel_hi:[1,0]
	v_pk_add_f32 v[66:67], v[64:65], 0 op_sel_hi:[1,0]
	v_cvt_pk_bf16_f32 v64, v68, v69
	v_cvt_pk_bf16_f32 v65, v70, v71
	v_pk_add_f32 v[16:17], v[16:17], 0 op_sel_hi:[1,0]
	v_cvt_pk_bf16_f32 v66, v66, v67
	v_cvt_pk_bf16_f32 v67, v72, v73
	ds_bpermute_b32 v244, v253, v64
	ds_bpermute_b32 v245, v253, v65
	ds_bpermute_b32 v246, v253, v66
	ds_bpermute_b32 v247, v253, v67
	v_lshl_add_u64 v[238:239], v[76:77], 0, v[248:249]
	s_waitcnt lgkmcnt(4)
	global_store_dwordx4 v[236:237], v[240:243], off
	v_pk_add_f32 v[6:7], v[6:7], 0 op_sel_hi:[1,0]
	v_pk_add_f32 v[4:5], v[4:5], 0 op_sel_hi:[1,0]
	v_pk_add_f32 v[66:67], v[58:59], 0 op_sel_hi:[1,0]
	v_pk_add_f32 v[58:59], v[56:57], 0 op_sel_hi:[1,0]
	v_cvt_pk_bf16_f32 v56, v60, v61
	v_add_co_u32_e32 v60, vcc, s55, v142
	v_cvt_pk_bf16_f32 v57, v62, v63
	v_cvt_pk_bf16_f32 v58, v58, v59
	v_cvt_pk_bf16_f32 v59, v66, v67
	v_lshl_add_u64 v[64:65], v[142:143], 0, s[14:15]
	s_nop 0
	v_addc_co_u32_e32 v61, vcc, 0, v143, vcc
	ds_bpermute_b32 v240, v253, v56
	ds_bpermute_b32 v241, v253, v57
	ds_bpermute_b32 v242, v253, v58
	ds_bpermute_b32 v243, v253, v59
	v_lshl_add_u64 v[236:237], v[60:61], 0, v[248:249]
	s_waitcnt lgkmcnt(4)
	global_store_dwordx4 v[238:239], v[244:247], off offset:256
	s_nop 1
	v_pk_add_f32 v[56:57], v[46:47], 0 op_sel_hi:[1,0]
	v_pk_add_f32 v[46:47], v[44:45], 0 op_sel_hi:[1,0]
	v_cvt_pk_bf16_f32 v44, v52, v53
	v_cvt_pk_bf16_f32 v45, v54, v55
	s_nop 0
	v_cvt_pk_bf16_f32 v46, v46, v47
	v_cvt_pk_bf16_f32 v47, v56, v57
	ds_bpermute_b32 v244, v253, v44
	ds_bpermute_b32 v245, v253, v45
	ds_bpermute_b32 v246, v253, v46
	ds_bpermute_b32 v247, v253, v47
	v_lshl_add_u64 v[238:239], v[64:65], 0, v[248:249]
	s_waitcnt lgkmcnt(4)
	global_store_dwordx4 v[236:237], v[240:243], off
	s_nop 1
	v_pk_add_f32 v[46:47], v[50:51], 0 op_sel_hi:[1,0]
	v_pk_add_f32 v[50:51], v[42:43], 0 op_sel_hi:[1,0]
	v_pk_add_f32 v[42:43], v[40:41], 0 op_sel_hi:[1,0]
	v_cvt_pk_bf16_f32 v40, v48, v49
	v_cvt_pk_bf16_f32 v41, v46, v47
	v_add_co_u32_e32 v46, vcc, s56, v142
	v_cvt_pk_bf16_f32 v42, v42, v43
	v_cvt_pk_bf16_f32 v43, v50, v51
	v_lshl_add_u64 v[44:45], v[142:143], 0, s[16:17]
	s_nop 0
	v_addc_co_u32_e32 v47, vcc, 0, v143, vcc
	ds_bpermute_b32 v240, v253, v40
	ds_bpermute_b32 v241, v253, v41
	ds_bpermute_b32 v242, v253, v42
	ds_bpermute_b32 v243, v253, v43
	v_lshl_add_u64 v[236:237], v[46:47], 0, v[248:249]
	s_waitcnt lgkmcnt(4)
	global_store_dwordx4 v[238:239], v[244:247], off offset:256
	s_nop 1
	v_pk_add_f32 v[40:41], v[30:31], 0 op_sel_hi:[1,0]
	v_pk_add_f32 v[30:31], v[28:29], 0 op_sel_hi:[1,0]
	v_cvt_pk_bf16_f32 v28, v36, v37
	v_cvt_pk_bf16_f32 v29, v38, v39
	s_nop 0
	v_cvt_pk_bf16_f32 v30, v30, v31
	v_cvt_pk_bf16_f32 v31, v40, v41
	ds_bpermute_b32 v244, v253, v28
	ds_bpermute_b32 v245, v253, v29
	ds_bpermute_b32 v246, v253, v30
	ds_bpermute_b32 v247, v253, v31
	v_lshl_add_u64 v[238:239], v[44:45], 0, v[248:249]
	s_waitcnt lgkmcnt(4)
	global_store_dwordx4 v[236:237], v[240:243], off
	s_nop 1
	v_pk_add_f32 v[30:31], v[34:35], 0 op_sel_hi:[1,0]
	v_pk_add_f32 v[34:35], v[26:27], 0 op_sel_hi:[1,0]
	v_pk_add_f32 v[26:27], v[24:25], 0 op_sel_hi:[1,0]
	v_cvt_pk_bf16_f32 v24, v32, v33
	v_cvt_pk_bf16_f32 v25, v30, v31
	v_add_co_u32_e32 v30, vcc, s57, v142
	v_cvt_pk_bf16_f32 v26, v26, v27
	v_cvt_pk_bf16_f32 v27, v34, v35
	v_lshl_add_u64 v[28:29], v[142:143], 0, s[18:19]
	s_nop 0
	v_addc_co_u32_e32 v31, vcc, 0, v143, vcc
	ds_bpermute_b32 v240, v253, v24
	ds_bpermute_b32 v241, v253, v25
	ds_bpermute_b32 v242, v253, v26
	ds_bpermute_b32 v243, v253, v27
	v_lshl_add_u64 v[236:237], v[30:31], 0, v[248:249]
	s_waitcnt lgkmcnt(4)
	global_store_dwordx4 v[238:239], v[244:247], off offset:256
	s_nop 1
	v_pk_add_f32 v[24:25], v[14:15], 0 op_sel_hi:[1,0]
	v_pk_add_f32 v[14:15], v[12:13], 0 op_sel_hi:[1,0]
	v_cvt_pk_bf16_f32 v12, v20, v21
	v_cvt_pk_bf16_f32 v13, v22, v23
	s_nop 0
	v_cvt_pk_bf16_f32 v14, v14, v15
	v_cvt_pk_bf16_f32 v15, v24, v25
	ds_bpermute_b32 v244, v253, v12
	ds_bpermute_b32 v245, v253, v13
	ds_bpermute_b32 v246, v253, v14
	ds_bpermute_b32 v247, v253, v15
	v_lshl_add_u64 v[238:239], v[28:29], 0, v[248:249]
	s_waitcnt lgkmcnt(4)
	global_store_dwordx4 v[236:237], v[240:243], off
	s_nop 1
	v_pk_add_f32 v[14:15], v[18:19], 0 op_sel_hi:[1,0]
	v_pk_add_f32 v[18:19], v[10:11], 0 op_sel_hi:[1,0]
	v_pk_add_f32 v[10:11], v[8:9], 0 op_sel_hi:[1,0]
	v_cvt_pk_bf16_f32 v8, v16, v17
	v_cvt_pk_bf16_f32 v9, v14, v15
	v_add_co_u32_e32 v14, vcc, s58, v142
	v_lshl_add_u64 v[12:13], v[142:143], 0, s[22:23]
	s_nop 0
	v_addc_co_u32_e32 v15, vcc, 0, v143, vcc
	v_cvt_pk_bf16_f32 v10, v10, v11
	v_cvt_pk_bf16_f32 v11, v18, v19
	ds_bpermute_b32 v240, v253, v8
	ds_bpermute_b32 v241, v253, v9
	ds_bpermute_b32 v242, v253, v10
	ds_bpermute_b32 v243, v253, v11
	v_lshl_add_u64 v[236:237], v[14:15], 0, v[248:249]
	s_waitcnt lgkmcnt(4)
	global_store_dwordx4 v[238:239], v[244:247], off offset:256
	s_andn2_b64 vcc, exec, s[24:25]
	s_mov_b64 s[24:25], -1
	v_pk_add_f32 v[8:9], v[2:3], 0 op_sel_hi:[1,0]
	v_pk_add_f32 v[2:3], v[0:1], 0 op_sel_hi:[1,0]
	v_cvt_pk_bf16_f32 v0, v4, v5
	v_cvt_pk_bf16_f32 v1, v6, v7
	s_nop 0
	v_cvt_pk_bf16_f32 v2, v2, v3
	v_cvt_pk_bf16_f32 v3, v8, v9
	ds_bpermute_b32 v244, v253, v0
	ds_bpermute_b32 v245, v253, v1
	ds_bpermute_b32 v246, v253, v2
	ds_bpermute_b32 v247, v253, v3
	v_lshl_add_u64 v[238:239], v[12:13], 0, v[248:249]
	s_waitcnt lgkmcnt(4)
	global_store_dwordx4 v[236:237], v[240:243], off
	s_waitcnt lgkmcnt(0)
	global_store_dwordx4 v[238:239], v[244:247], off offset:256
	s_cbranch_vccnz .LBB0_830
	s_andn2_b64 vcc, exec, s[4:5]
	s_cbranch_vccnz .LBB0_829
	s_barrier
	s_branch .LBB0_829
